# mixers: batched the spatial-gating epilogue u-loads, pooling epilogue pool_scale loads and the 128x128 weight staging loads (were serialized load-wait-use chains)
# baseline (speedup 1.0000x reference)
.LBB0_549:
	s_or_b64 exec, exec, s[22:23]
	ds_read_b128 v[12:15], v40 offset:2224
	s_ashr_i32 s23, s48, 31
	s_ashr_i32 s28, s49, 31
	s_add_u32 s22, s49, s48
	s_addc_u32 s23, s28, s23
	s_waitcnt lgkmcnt(0)
	v_lshlrev_b32_e32 v8, 16, v12
	v_fma_f32 v7, v10, v7, -v8
	v_and_b32_e32 v8, 0xffff0000, v12
	v_fma_f32 v6, v10, v6, -v8
	v_lshlrev_b32_e32 v8, 16, v13
	v_fma_f32 v5, v10, v5, -v8
	v_and_b32_e32 v8, 0xffff0000, v13
	v_fma_f32 v4, v10, v4, -v8
	v_lshlrev_b32_e32 v8, 16, v14
	v_fma_f32 v3, v10, v3, -v8
	v_and_b32_e32 v8, 0xffff0000, v14
	v_fma_f32 v2, v10, v2, -v8
	v_lshlrev_b32_e32 v8, 16, v15
	v_fma_f32 v8, v10, v1, -v8
	v_and_b32_e32 v1, 0xffff0000, v15
	v_fma_f32 v9, v10, v0, -v1
	v_cvt_pk_bf16_f32 v0, v7, v6
	v_cvt_pk_bf16_f32 v1, v5, v4
	v_cvt_pk_bf16_f32 v2, v3, v2
	v_cvt_pk_bf16_f32 v3, v8, v9
	ds_write_b128 v41, v[0:3] offset:48
	s_waitcnt lgkmcnt(0)
	s_barrier
	ds_read_b128 v[0:3], v34
	ds_read_b128 v[4:7], v47 offset:34816
	ds_read_b128 v[8:11], v47 offset:39168
	ds_read_b128 v[12:15], v47 offset:43520
	ds_read_b128 v[18:21], v47 offset:47872
	ds_read_b128 v[22:25], v47 offset:52224
	ds_read_b128 v[26:29], v47 offset:56576
	ds_read_b128 v[30:33], v47 offset:60928
	ds_read_b128 v[48:51], v47 offset:65280
	s_waitcnt lgkmcnt(7)
	v_mfma_f32_16x16x32_bf16 v[4:7], v[4:7], v[0:3], 0
	v_lshl_or_b32 v16, s47, 7, v35
	s_waitcnt lgkmcnt(6)
	v_mfma_f32_16x16x32_bf16 v[8:11], v[8:11], v[0:3], 0
	s_waitcnt lgkmcnt(5)
	v_mfma_f32_16x16x32_bf16 v[12:15], v[12:15], v[0:3], 0
	s_waitcnt lgkmcnt(4)
	v_mfma_f32_16x16x32_bf16 v[18:21], v[18:21], v[0:3], 0
	s_waitcnt lgkmcnt(3)
	v_mfma_f32_16x16x32_bf16 v[22:25], v[22:25], v[0:3], 0
	s_waitcnt lgkmcnt(2)
	v_mfma_f32_16x16x32_bf16 v[26:29], v[26:29], v[0:3], 0
	s_waitcnt lgkmcnt(1)
	v_mfma_f32_16x16x32_bf16 v[30:33], v[30:33], v[0:3], 0
	s_waitcnt lgkmcnt(0)
	v_mfma_f32_16x16x32_bf16 v[0:3], v[48:51], v[0:3], 0
	ds_read_b128 v[48:51], v34 offset:64
	ds_read_b128 v[52:55], v47 offset:34880
	s_waitcnt lgkmcnt(0)
	v_mfma_f32_16x16x32_bf16 v[4:7], v[52:55], v[48:51], v[4:7]
	ds_read_b128 v[52:55], v47 offset:39232
	s_waitcnt lgkmcnt(0)
	v_mfma_f32_16x16x32_bf16 v[8:11], v[52:55], v[48:51], v[8:11]
	ds_read_b128 v[52:55], v47 offset:43584
	s_waitcnt lgkmcnt(0)
	v_mfma_f32_16x16x32_bf16 v[12:15], v[52:55], v[48:51], v[12:15]
	ds_read_b128 v[52:55], v47 offset:47936
	s_waitcnt lgkmcnt(0)
	v_mfma_f32_16x16x32_bf16 v[18:21], v[52:55], v[48:51], v[18:21]
	ds_read_b128 v[52:55], v47 offset:52288
	s_waitcnt lgkmcnt(0)
	v_mfma_f32_16x16x32_bf16 v[22:25], v[52:55], v[48:51], v[22:25]
	ds_read_b128 v[52:55], v47 offset:56640
	s_waitcnt lgkmcnt(0)
	v_mfma_f32_16x16x32_bf16 v[26:29], v[52:55], v[48:51], v[26:29]
	ds_read_b128 v[52:55], v47 offset:60992
	s_waitcnt lgkmcnt(0)
	v_mfma_f32_16x16x32_bf16 v[30:33], v[52:55], v[48:51], v[30:33]
	ds_read_b128 v[52:55], v47 offset:65344
	s_waitcnt lgkmcnt(0)
	v_mfma_f32_16x16x32_bf16 v[0:3], v[52:55], v[48:51], v[0:3]
	ds_read_b128 v[48:51], v34 offset:128
	ds_read_b128 v[52:55], v47 offset:34944
	s_waitcnt lgkmcnt(0)
	v_mfma_f32_16x16x32_bf16 v[4:7], v[52:55], v[48:51], v[4:7]
	ds_read_b128 v[52:55], v47 offset:39296
	s_waitcnt lgkmcnt(0)
	v_mfma_f32_16x16x32_bf16 v[8:11], v[52:55], v[48:51], v[8:11]
	ds_read_b128 v[52:55], v47 offset:43648
	s_waitcnt lgkmcnt(0)
	v_mfma_f32_16x16x32_bf16 v[12:15], v[52:55], v[48:51], v[12:15]
	ds_read_b128 v[52:55], v47 offset:48000
	s_waitcnt lgkmcnt(0)
	v_mfma_f32_16x16x32_bf16 v[18:21], v[52:55], v[48:51], v[18:21]
	ds_read_b128 v[52:55], v47 offset:52352
	s_waitcnt lgkmcnt(0)
	v_mfma_f32_16x16x32_bf16 v[52:55], v[52:55], v[48:51], v[22:25]
	s_nop 2
	ds_read_b128 v[22:25], v47 offset:56704
	s_waitcnt lgkmcnt(0)
	v_mfma_f32_16x16x32_bf16 v[56:59], v[22:25], v[48:51], v[26:29]
	ds_read_b128 v[22:25], v47 offset:61056
	s_waitcnt lgkmcnt(0)
	v_mfma_f32_16x16x32_bf16 v[60:63], v[22:25], v[48:51], v[30:33]
	ds_read_b128 v[22:25], v47 offset:65408
	s_waitcnt lgkmcnt(0)
	v_mfma_f32_16x16x32_bf16 v[0:3], v[22:25], v[48:51], v[0:3]
	ds_read_b128 v[48:51], v34 offset:192
	ds_read_b128 v[22:25], v47 offset:35008
	s_waitcnt lgkmcnt(0)
	v_mfma_f32_16x16x32_bf16 v[30:33], v[22:25], v[48:51], v[4:7]
	s_nop 2
	ds_read_b128 v[4:7], v47 offset:39360
	s_waitcnt lgkmcnt(0)
	v_mfma_f32_16x16x32_bf16 v[26:29], v[4:7], v[48:51], v[8:11]
	ds_read_b128 v[4:7], v47 offset:43712
	s_waitcnt lgkmcnt(0)
	v_mfma_f32_16x16x32_bf16 v[22:25], v[4:7], v[48:51], v[12:15]
	ds_read_b128 v[4:7], v47 offset:48064
	s_waitcnt lgkmcnt(0)
	v_mfma_f32_16x16x32_bf16 v[18:21], v[4:7], v[48:51], v[18:21]
	ds_read_b128 v[4:7], v47 offset:52416
	s_waitcnt lgkmcnt(0)
	v_mfma_f32_16x16x32_bf16 v[12:15], v[4:7], v[48:51], v[52:55]
	ds_read_b128 v[4:7], v47 offset:56768
	s_nop 1
	ds_read_b128 v[52:55], v47 offset:65472
	s_waitcnt lgkmcnt(1)
	v_mfma_f32_16x16x32_bf16 v[8:11], v[4:7], v[48:51], v[56:59]
	ds_read_b128 v[4:7], v47 offset:61120
	s_waitcnt lgkmcnt(0)
	v_mfma_f32_16x16x32_bf16 v[4:7], v[4:7], v[48:51], v[60:63]
	v_mfma_f32_16x16x32_bf16 v[0:3], v[52:55], v[48:51], v[0:3]
	v_lshl_add_u64 v[48:49], s[22:23], 0, v[36:37]
	v_lshlrev_b64 v[48:49], 12, v[48:49]
	v_lshlrev_b32_e32 v54, 2, v16
	v_lshl_add_u64 v[52:53], s[0:1], 0, v[48:49]
	global_load_dwordx4 v[48:51], v54, s[18:19]
	global_load_dwordx4 v[164:167], v54, s[18:19] offset:64
	global_load_dwordx4 v[168:171], v54, s[18:19] offset:128
	global_load_dwordx4 v[172:175], v54, s[18:19] offset:192
	global_load_dwordx4 v[176:179], v54, s[18:19] offset:256
	global_load_dwordx4 v[180:183], v54, s[18:19] offset:320
	global_load_dwordx4 v[184:187], v54, s[18:19] offset:384
	global_load_dwordx4 v[188:191], v54, s[18:19] offset:448
	v_lshlrev_b32_e32 v16, 1, v16
	s_waitcnt vmcnt(0)
	v_mul_f32_e32 v30, v30, v48
	v_mul_f32_e32 v31, v31, v49
	v_cvt_pk_bf16_f32 v30, v30, v31
	v_mul_f32_e32 v31, v32, v50
	v_lshl_add_u64 v[48:49], v[52:53], 0, v[16:17]
	v_mul_f32_e32 v32, v33, v51
	v_cvt_pk_bf16_f32 v31, v31, v32
	global_store_dwordx2 v[48:49], v[30:31], off
	v_mul_f32_e32 v16, v26, v164
	v_mul_f32_e32 v26, v27, v165
	v_mul_f32_e32 v27, v29, v167
	v_cvt_pk_bf16_f32 v26, v16, v26
	v_mul_f32_e32 v16, v28, v166
	v_cvt_pk_bf16_f32 v27, v16, v27
	global_store_dwordx2 v[48:49], v[26:27], off offset:32
	v_mul_f32_e32 v16, v22, v168
	v_mul_f32_e32 v22, v23, v169
	v_mul_f32_e32 v23, v25, v171
	v_cvt_pk_bf16_f32 v22, v16, v22
	v_mul_f32_e32 v16, v24, v170
	v_cvt_pk_bf16_f32 v23, v16, v23
	global_store_dwordx2 v[48:49], v[22:23], off offset:64
	v_mul_f32_e32 v16, v18, v172
	v_mul_f32_e32 v18, v19, v173
	v_mul_f32_e32 v19, v21, v175
	v_cvt_pk_bf16_f32 v18, v16, v18
	v_mul_f32_e32 v16, v20, v174
	v_cvt_pk_bf16_f32 v19, v16, v19
	global_store_dwordx2 v[48:49], v[18:19], off offset:96
	v_mul_f32_e32 v12, v12, v176
	v_mul_f32_e32 v13, v13, v177
	v_cvt_pk_bf16_f32 v12, v12, v13
	v_mul_f32_e32 v13, v14, v178
	v_mul_f32_e32 v14, v15, v179
	v_cvt_pk_bf16_f32 v13, v13, v14
	global_store_dwordx2 v[48:49], v[12:13], off offset:128
	v_mul_f32_e32 v8, v8, v180
	v_mul_f32_e32 v9, v9, v181
	v_cvt_pk_bf16_f32 v8, v8, v9
	v_mul_f32_e32 v9, v10, v182
	v_mul_f32_e32 v10, v11, v183
	v_cvt_pk_bf16_f32 v9, v9, v10
	global_store_dwordx2 v[48:49], v[8:9], off offset:160
	v_mul_f32_e32 v4, v4, v184
	v_mul_f32_e32 v5, v5, v185
	v_cvt_pk_bf16_f32 v4, v4, v5
	v_mul_f32_e32 v5, v6, v186
	v_mul_f32_e32 v6, v7, v187
	v_cvt_pk_bf16_f32 v5, v5, v6
	global_store_dwordx2 v[48:49], v[4:5], off offset:192
	v_mul_f32_e32 v0, v0, v188
	v_mul_f32_e32 v1, v1, v189
	v_cvt_pk_bf16_f32 v0, v0, v1
	v_mul_f32_e32 v1, v2, v190
	v_mul_f32_e32 v2, v3, v191
	v_cvt_pk_bf16_f32 v1, v1, v2
	global_store_dwordx2 v[48:49], v[0:1], off offset:224
	s_barrier

.LBB0_556:
	s_and_b32 s47, s26, 3
	s_lshl_b32 s22, s47, 15
	v_mov_b32_e32 v7, v208
	s_add_u32 s22, s37, s22
	s_addc_u32 s23, s44, 0
	v_lshlrev_b32_e32 v0, 4, v7
	v_ashrrev_i32_e32 v8, 4, v7
	v_and_b32_e32 v16, 0xf0, v0
	v_lshlrev_b32_e32 v0, 7, v8
	v_lshl_add_u64 v[4:5], s[22:23], 0, v[16:17]
	v_ashrrev_i32_e32 v1, 31, v0
	v_lshl_add_u64 v[0:1], v[0:1], 1, v[4:5]
	global_load_dwordx4 v[192:195], v[0:1], off
	v_add_u32_e32 v6, 0, v16
	v_mad_u64_u32 v[8:9], s[22:23], v8, s80, v[6:7]
	v_mov_b32_e32 v156, v8
	v_add_u32_e32 v0, 0x200, v7
	v_ashrrev_i32_e32 v8, 4, v0
	v_lshlrev_b32_e32 v0, 7, v8
	v_ashrrev_i32_e32 v1, 31, v0
	v_lshl_add_u64 v[0:1], v[0:1], 1, v[4:5]
	global_load_dwordx4 v[196:199], v[0:1], off
	v_mad_u64_u32 v[8:9], s[22:23], v8, s80, v[6:7]
	v_mov_b32_e32 v157, v8
	v_add_u32_e32 v0, 0x400, v7
	v_ashrrev_i32_e32 v8, 4, v0
	v_lshlrev_b32_e32 v0, 7, v8
	v_ashrrev_i32_e32 v1, 31, v0
	v_lshl_add_u64 v[0:1], v[0:1], 1, v[4:5]
	global_load_dwordx4 v[200:203], v[0:1], off
	v_mad_u64_u32 v[8:9], s[22:23], v8, s80, v[6:7]
	v_mov_b32_e32 v158, v8
	v_add_u32_e32 v0, 0x600, v7
	v_ashrrev_i32_e32 v7, 4, v0
	v_lshlrev_b32_e32 v0, 7, v7
	v_ashrrev_i32_e32 v1, 31, v0
	v_lshl_add_u64 v[0:1], v[0:1], 1, v[4:5]
	global_load_dwordx4 v[204:207], v[0:1], off
	v_mad_u64_u32 v[4:5], s[22:23], v7, s80, v[6:7]
	v_mov_b32_e32 v159, v4
	s_waitcnt vmcnt(0)
	ds_write_b128 v156, v[192:195] offset:34816
	ds_write_b128 v157, v[196:199] offset:34816
	ds_write_b128 v158, v[200:203] offset:34816
	ds_write_b128 v159, v[204:207] offset:34816
	s_and_saveexec_b64 s[22:23], s[38:39]
	s_cbranch_execz .LBB0_561
	s_add_i32 s51, s49, -8
	s_lshl_b32 s28, s47, 8
	s_add_u32 s28, s27, s28
	s_addc_u32 s29, s36, 0
	s_mov_b64 s[40:41], 0
	v_mov_b32_e32 v4, v42
	v_mov_b32_e32 v5, v38
	s_branch .LBB0_559

.LBB0_579:
	s_and_b32 s26, s36, 3
	s_lshl_b32 s24, s26, 15
	v_mov_b32_e32 v7, v208
	s_add_u32 s40, s37, s24
	s_addc_u32 s41, s38, 0
	v_lshlrev_b32_e32 v0, 4, v7
	v_and_b32_e32 v16, 0xf0, v0
	v_lshl_add_u64 v[0:1], s[40:41], 0, v[16:17]
	s_mov_b64 s[40:41], 0x298000
	v_ashrrev_i32_e32 v8, 4, v7
	v_lshl_add_u64 v[4:5], v[0:1], 0, s[40:41]
	v_lshlrev_b32_e32 v0, 7, v8
	v_ashrrev_i32_e32 v1, 31, v0
	v_lshl_add_u64 v[0:1], v[0:1], 1, v[4:5]
	global_load_dwordx4 v[192:195], v[0:1], off
	v_add_u32_e32 v6, 0, v16
	v_mad_u64_u32 v[8:9], s[40:41], v8, s80, v[6:7]
	s_add_i32 s24, s29, s28
	v_mov_b32_e32 v41, v17
	v_cmp_lt_i32_e32 vcc, v214, v212
	v_mov_b32_e32 v43, v17
	s_lshl_b32 s27, s26, 7
	v_mov_b32_e32 v156, v8
	v_add_u32_e32 v0, 0x200, v7
	v_ashrrev_i32_e32 v8, 4, v0
	v_lshlrev_b32_e32 v0, 7, v8
	v_ashrrev_i32_e32 v1, 31, v0
	v_lshl_add_u64 v[0:1], v[0:1], 1, v[4:5]
	global_load_dwordx4 v[196:199], v[0:1], off
	v_mad_u64_u32 v[8:9], s[40:41], v8, s80, v[6:7]
	v_mov_b32_e32 v157, v8
	v_add_u32_e32 v0, 0x400, v7
	v_ashrrev_i32_e32 v8, 4, v0
	v_lshlrev_b32_e32 v0, 7, v8
	v_ashrrev_i32_e32 v1, 31, v0
	v_lshl_add_u64 v[0:1], v[0:1], 1, v[4:5]
	global_load_dwordx4 v[200:203], v[0:1], off
	v_mad_u64_u32 v[8:9], s[40:41], v8, s80, v[6:7]
	v_mov_b32_e32 v158, v8
	v_add_u32_e32 v0, 0x600, v7
	v_ashrrev_i32_e32 v7, 4, v0
	v_lshlrev_b32_e32 v0, 7, v7
	v_ashrrev_i32_e32 v1, 31, v0
	v_lshl_add_u64 v[0:1], v[0:1], 1, v[4:5]
	global_load_dwordx4 v[204:207], v[0:1], off
	v_mad_u64_u32 v[4:5], s[40:41], v7, s80, v[6:7]
	v_mov_b32_e32 v159, v4
	s_waitcnt vmcnt(0)
	ds_write_b128 v156, v[192:195]
	ds_write_b128 v157, v[196:199]
	ds_write_b128 v158, v[200:203]
	ds_write_b128 v159, v[204:207]
	v_add_u32_e32 v0, s24, v72
	v_ashrrev_i32_e32 v1, 31, v0
	v_lshlrev_b64 v[0:1], 13, v[0:1]
	v_lshl_add_u64 v[18:19], s[22:23], 0, v[0:1]
	v_lshl_add_u64 v[20:21], v[18:19], 0, v[40:41]
	global_load_dwordx4 v[0:3], v[20:21], off offset:2096
	global_load_dwordx4 v[4:7], v[20:21], off offset:2080
	global_load_dwordx4 v[8:11], v[20:21], off offset:2064
	global_load_dwordx4 v[12:15], v[20:21], off offset:2048
	s_mov_b32 s24, 0x3b000000
	s_waitcnt vmcnt(2)
	v_lshlrev_b32_e32 v59, 16, v4
	s_waitcnt vmcnt(1)
	v_lshlrev_b32_e32 v47, 16, v8
	s_waitcnt vmcnt(0)
	v_and_b32_e32 v25, 0xffff0000, v13
	v_lshlrev_b32_e32 v13, 16, v13
	v_and_b32_e32 v23, 0xffff0000, v12
	v_lshlrev_b32_e32 v12, 16, v12
	v_mov_b32_e32 v16, v13
	v_pk_mul_f32 v[28:29], v[12:13], v[16:17] op_sel:[1,0] op_sel_hi:[0,1]
	v_pk_add_f32 v[30:31], v[12:13], v[22:23] op_sel:[1,0] op_sel_hi:[0,1]
	v_mul_f32_e32 v26, v12, v12
	v_mov_b32_e32 v29, v31
	v_mul_f32_e32 v16, v25, v25
	v_lshlrev_b32_e32 v31, 16, v14
	v_and_b32_e32 v33, 0xffff0000, v14
	v_mov_b32_e32 v27, v13
	v_mul_f32_e32 v24, v23, v23
	v_mul_f32_e32 v30, v31, v31
	v_mul_f32_e32 v32, v33, v33
	v_lshlrev_b32_e32 v45, 16, v15
	v_and_b32_e32 v15, 0xffff0000, v15
	v_pk_add_f32 v[12:13], v[26:27], v[24:25]
	v_pk_add_f32 v[22:23], v[28:29], v[16:17]
	v_mul_f32_e32 v44, v45, v45
	v_mul_f32_e32 v14, v15, v15
	v_and_b32_e32 v49, 0xffff0000, v8
	v_pk_add_f32 v[12:13], v[12:13], v[22:23]
	v_pk_add_f32 v[22:23], v[30:31], v[32:33]
	v_mul_f32_e32 v46, v47, v47
	v_mul_f32_e32 v48, v49, v49
	v_lshlrev_b32_e32 v51, 16, v9
	v_and_b32_e32 v9, 0xffff0000, v9
	v_pk_add_f32 v[12:13], v[22:23], v[12:13]
	v_pk_add_f32 v[14:15], v[44:45], v[14:15]
	v_mul_f32_e32 v50, v51, v51
	v_mul_f32_e32 v8, v9, v9
	v_lshlrev_b32_e32 v53, 16, v10
	v_and_b32_e32 v55, 0xffff0000, v10
	v_pk_add_f32 v[12:13], v[14:15], v[12:13]
	v_pk_add_f32 v[14:15], v[46:47], v[48:49]
	v_mul_f32_e32 v52, v53, v53
	v_mul_f32_e32 v54, v55, v55
	v_lshlrev_b32_e32 v57, 16, v11
	v_and_b32_e32 v11, 0xffff0000, v11
	v_pk_add_f32 v[12:13], v[14:15], v[12:13]
	v_pk_add_f32 v[8:9], v[50:51], v[8:9]
	v_mul_f32_e32 v56, v57, v57
	v_mul_f32_e32 v10, v11, v11
	v_and_b32_e32 v61, 0xffff0000, v4
	v_pk_add_f32 v[8:9], v[8:9], v[12:13]
	v_pk_add_f32 v[12:13], v[52:53], v[54:55]
	v_mul_f32_e32 v58, v59, v59
	v_mul_f32_e32 v60, v61, v61
	v_lshlrev_b32_e32 v63, 16, v5
	v_and_b32_e32 v5, 0xffff0000, v5
	v_pk_add_f32 v[8:9], v[12:13], v[8:9]
	v_pk_add_f32 v[10:11], v[56:57], v[10:11]
	v_mul_f32_e32 v62, v63, v63
	v_mul_f32_e32 v4, v5, v5
	v_lshlrev_b32_e32 v65, 16, v6
	v_and_b32_e32 v67, 0xffff0000, v6
	v_pk_add_f32 v[8:9], v[10:11], v[8:9]
	v_pk_add_f32 v[10:11], v[58:59], v[60:61]
	v_mul_f32_e32 v64, v65, v65
	v_mul_f32_e32 v66, v67, v67
	v_pk_add_f32 v[8:9], v[10:11], v[8:9]
	v_pk_add_f32 v[4:5], v[62:63], v[4:5]
	v_lshlrev_b32_e32 v27, 16, v0
	v_pk_add_f32 v[4:5], v[4:5], v[8:9]
	v_pk_add_f32 v[8:9], v[64:65], v[66:67]
	v_and_b32_e32 v29, 0xffff0000, v0
	v_pk_add_f32 v[22:23], v[8:9], v[4:5]
	v_lshlrev_b32_e32 v5, 16, v7
	v_and_b32_e32 v7, 0xffff0000, v7
	v_mul_f32_e32 v4, v5, v5
	v_mul_f32_e32 v6, v7, v7
	v_pk_add_f32 v[24:25], v[4:5], v[6:7]
	v_lshlrev_b32_e32 v31, 16, v1
	v_and_b32_e32 v33, 0xffff0000, v1
	v_lshlrev_b32_e32 v45, 16, v2
	v_and_b32_e32 v47, 0xffff0000, v2
	v_lshlrev_b32_e32 v49, 16, v3
	v_and_b32_e32 v51, 0xffff0000, v3
	global_load_dwordx4 v[0:3], v[20:21], off offset:2160
	global_load_dwordx4 v[4:7], v[20:21], off offset:2144
	global_load_dwordx4 v[8:11], v[20:21], off offset:2128
	global_load_dwordx4 v[12:15], v[20:21], off offset:2112
	v_mul_f32_e32 v26, v27, v27
	v_mul_f32_e32 v28, v29, v29
	v_mul_f32_e32 v30, v31, v31
	v_mul_f32_e32 v32, v33, v33
	v_pk_add_f32 v[22:23], v[24:25], v[22:23]
	v_pk_add_f32 v[24:25], v[26:27], v[28:29]
	v_mul_f32_e32 v44, v45, v45
	v_mul_f32_e32 v46, v47, v47
	v_pk_add_f32 v[22:23], v[24:25], v[22:23]
	v_pk_add_f32 v[24:25], v[30:31], v[32:33]
	v_mul_f32_e32 v48, v49, v49
	v_mul_f32_e32 v50, v51, v51
	v_pk_add_f32 v[22:23], v[24:25], v[22:23]
	v_pk_add_f32 v[24:25], v[44:45], v[46:47]
	v_cndmask_b32_e32 v16, v211, v214, vcc
	v_pk_add_f32 v[22:23], v[24:25], v[22:23]
	v_pk_add_f32 v[24:25], v[48:49], v[50:51]
	v_lshlrev_b32_e32 v16, 2, v16
	v_pk_add_f32 v[22:23], v[24:25], v[22:23]
	v_cmp_lt_i32_e32 vcc, v215, v212
	s_waitcnt vmcnt(3)
	v_lshlrev_b32_e32 v45, 16, v0
	s_waitcnt vmcnt(2)
	v_lshlrev_b32_e32 v49, 16, v7
	s_waitcnt vmcnt(1)
	v_lshlrev_b32_e32 v65, 16, v8
	s_waitcnt vmcnt(0)
	v_lshlrev_b32_e32 v53, 16, v12
	v_and_b32_e32 v55, 0xffff0000, v12
	v_mul_f32_e32 v52, v53, v53
	v_mul_f32_e32 v54, v55, v55
	v_lshlrev_b32_e32 v57, 16, v13
	v_and_b32_e32 v13, 0xffff0000, v13
	v_mul_f32_e32 v56, v57, v57
	v_mul_f32_e32 v12, v13, v13
	v_lshlrev_b32_e32 v59, 16, v14
	v_and_b32_e32 v61, 0xffff0000, v14
	v_pk_add_f32 v[24:25], v[52:53], v[54:55]
	v_mul_f32_e32 v58, v59, v59
	v_mul_f32_e32 v60, v61, v61
	v_lshlrev_b32_e32 v63, 16, v15
	v_and_b32_e32 v15, 0xffff0000, v15
	v_pk_add_f32 v[22:23], v[24:25], v[22:23]
	v_pk_add_f32 v[12:13], v[56:57], v[12:13]
	v_mul_f32_e32 v62, v63, v63
	v_mul_f32_e32 v14, v15, v15
	v_and_b32_e32 v67, 0xffff0000, v8
	v_pk_add_f32 v[12:13], v[12:13], v[22:23]
	v_pk_add_f32 v[22:23], v[58:59], v[60:61]
	v_mul_f32_e32 v64, v65, v65
	v_mul_f32_e32 v66, v67, v67
	v_lshlrev_b32_e32 v69, 16, v9
	v_and_b32_e32 v9, 0xffff0000, v9
	v_pk_add_f32 v[12:13], v[22:23], v[12:13]
	v_pk_add_f32 v[14:15], v[62:63], v[14:15]
	v_mul_f32_e32 v68, v69, v69
	v_mul_f32_e32 v8, v9, v9
	v_pk_add_f32 v[12:13], v[14:15], v[12:13]
	v_pk_add_f32 v[14:15], v[64:65], v[66:67]
	v_pk_add_f32 v[8:9], v[68:69], v[8:9]
	v_pk_add_f32 v[12:13], v[14:15], v[12:13]
	v_lshlrev_b32_e32 v67, 16, v11
	v_pk_add_f32 v[62:63], v[8:9], v[12:13]
	v_lshlrev_b32_e32 v9, 16, v10
	v_and_b32_e32 v13, 0xffff0000, v10
	v_mul_f32_e32 v8, v9, v9
	v_mul_f32_e32 v12, v13, v13
	v_pk_add_f32 v[70:71], v[8:9], v[12:13]
	v_and_b32_e32 v69, 0xffff0000, v11
	v_lshlrev_b32_e32 v61, 16, v4
	v_and_b32_e32 v65, 0xffff0000, v4
	v_lshlrev_b32_e32 v57, 16, v5
	v_and_b32_e32 v59, 0xffff0000, v5
	v_lshlrev_b32_e32 v53, 16, v6
	v_and_b32_e32 v55, 0xffff0000, v6
	v_and_b32_e32 v51, 0xffff0000, v7
	v_and_b32_e32 v47, 0xffff0000, v0
	v_lshlrev_b32_e32 v31, 16, v1
	v_and_b32_e32 v33, 0xffff0000, v1
	v_lshlrev_b32_e32 v27, 16, v2
	v_and_b32_e32 v29, 0xffff0000, v2
	v_lshlrev_b32_e32 v23, 16, v3
	v_and_b32_e32 v25, 0xffff0000, v3
	global_load_dwordx4 v[0:3], v[20:21], off offset:2224
	global_load_dwordx4 v[4:7], v[20:21], off offset:2208
	global_load_dwordx4 v[8:11], v[20:21], off offset:2192
	global_load_dwordx4 v[12:15], v[20:21], off offset:2176
	v_mul_f32_e32 v66, v67, v67
	v_mul_f32_e32 v68, v69, v69
	v_mul_f32_e32 v60, v61, v61
	v_mul_f32_e32 v64, v65, v65
	v_pk_add_f32 v[62:63], v[70:71], v[62:63]
	v_pk_add_f32 v[66:67], v[66:67], v[68:69]
	v_mul_f32_e32 v56, v57, v57
	v_mul_f32_e32 v58, v59, v59
	v_pk_add_f32 v[62:63], v[66:67], v[62:63]
	v_pk_add_f32 v[60:61], v[60:61], v[64:65]
	v_mul_f32_e32 v52, v53, v53
	v_mul_f32_e32 v54, v55, v55
	v_pk_add_f32 v[60:61], v[60:61], v[62:63]
	v_pk_add_f32 v[56:57], v[56:57], v[58:59]
	v_mul_f32_e32 v48, v49, v49
	v_mul_f32_e32 v50, v51, v51
	v_pk_add_f32 v[56:57], v[56:57], v[60:61]
	v_pk_add_f32 v[52:53], v[52:53], v[54:55]
	v_mul_f32_e32 v44, v45, v45
	v_mul_f32_e32 v46, v47, v47
	v_pk_add_f32 v[52:53], v[52:53], v[56:57]
	v_pk_add_f32 v[48:49], v[48:49], v[50:51]
	v_mul_f32_e32 v30, v31, v31
	v_mul_f32_e32 v32, v33, v33
	v_pk_add_f32 v[48:49], v[48:49], v[52:53]
	v_pk_add_f32 v[44:45], v[44:45], v[46:47]
	v_mul_f32_e32 v26, v27, v27
	v_mul_f32_e32 v28, v29, v29
	v_pk_add_f32 v[44:45], v[44:45], v[48:49]
	v_pk_add_f32 v[30:31], v[30:31], v[32:33]
	v_mul_f32_e32 v22, v23, v23
	v_mul_f32_e32 v24, v25, v25
	v_pk_add_f32 v[30:31], v[30:31], v[44:45]
	v_pk_add_f32 v[26:27], v[26:27], v[28:29]
	v_pk_add_f32 v[22:23], v[22:23], v[24:25]
	v_pk_add_f32 v[26:27], v[26:27], v[30:31]
	v_cndmask_b32_e32 v41, v211, v215, vcc
	v_pk_add_f32 v[22:23], v[22:23], v[26:27]
	v_lshlrev_b32_e32 v41, 2, v41
	s_waitcnt vmcnt(2)
	v_lshlrev_b32_e32 v53, 16, v4
	s_waitcnt vmcnt(1)
	v_lshlrev_b32_e32 v31, 16, v8
	s_waitcnt vmcnt(0)
	v_lshlrev_b32_e32 v81, 16, v12
	v_and_b32_e32 v83, 0xffff0000, v12
	v_mul_f32_e32 v80, v81, v81
	v_mul_f32_e32 v82, v83, v83
	v_pk_add_f32 v[24:25], v[80:81], v[82:83]
	v_and_b32_e32 v27, 0xffff0000, v14
	v_pk_add_f32 v[22:23], v[24:25], v[22:23]
	v_lshlrev_b32_e32 v25, 16, v13
	v_and_b32_e32 v13, 0xffff0000, v13
	v_mul_f32_e32 v24, v25, v25
	v_mul_f32_e32 v12, v13, v13
	v_pk_add_f32 v[12:13], v[24:25], v[12:13]
	v_lshlrev_b32_e32 v25, 16, v14
	v_mul_f32_e32 v24, v25, v25
	v_mul_f32_e32 v26, v27, v27
	v_lshlrev_b32_e32 v29, 16, v15
	v_and_b32_e32 v15, 0xffff0000, v15
	v_mul_f32_e32 v28, v29, v29
	v_mul_f32_e32 v14, v15, v15
	v_and_b32_e32 v33, 0xffff0000, v8
	v_pk_add_f32 v[12:13], v[12:13], v[22:23]
	v_pk_add_f32 v[22:23], v[24:25], v[26:27]
	v_mul_f32_e32 v30, v31, v31
	v_mul_f32_e32 v32, v33, v33
	v_lshlrev_b32_e32 v45, 16, v9
	v_and_b32_e32 v9, 0xffff0000, v9
	v_pk_add_f32 v[12:13], v[22:23], v[12:13]
	v_pk_add_f32 v[14:15], v[28:29], v[14:15]
	v_mul_f32_e32 v44, v45, v45
	v_mul_f32_e32 v8, v9, v9
	v_lshlrev_b32_e32 v47, 16, v10
	v_and_b32_e32 v49, 0xffff0000, v10
	v_pk_add_f32 v[12:13], v[14:15], v[12:13]
	v_pk_add_f32 v[14:15], v[30:31], v[32:33]
	v_mul_f32_e32 v46, v47, v47
	v_mul_f32_e32 v48, v49, v49
	v_lshlrev_b32_e32 v51, 16, v11
	v_and_b32_e32 v11, 0xffff0000, v11
	v_pk_add_f32 v[12:13], v[14:15], v[12:13]
	v_pk_add_f32 v[8:9], v[44:45], v[8:9]
	v_mul_f32_e32 v50, v51, v51
	v_mul_f32_e32 v10, v11, v11
	v_and_b32_e32 v55, 0xffff0000, v4
	v_pk_add_f32 v[8:9], v[8:9], v[12:13]
	v_pk_add_f32 v[12:13], v[46:47], v[48:49]
	v_mul_f32_e32 v52, v53, v53
	v_mul_f32_e32 v54, v55, v55
	v_lshlrev_b32_e32 v57, 16, v5
	v_and_b32_e32 v5, 0xffff0000, v5
	v_pk_add_f32 v[8:9], v[12:13], v[8:9]
	v_pk_add_f32 v[10:11], v[50:51], v[10:11]
	v_mul_f32_e32 v56, v57, v57
	v_mul_f32_e32 v4, v5, v5
	v_lshlrev_b32_e32 v59, 16, v6
	v_and_b32_e32 v61, 0xffff0000, v6
	v_pk_add_f32 v[8:9], v[10:11], v[8:9]
	v_pk_add_f32 v[10:11], v[52:53], v[54:55]
	v_mul_f32_e32 v58, v59, v59
	v_mul_f32_e32 v60, v61, v61
	v_lshlrev_b32_e32 v63, 16, v7
	v_and_b32_e32 v7, 0xffff0000, v7
	v_pk_add_f32 v[8:9], v[10:11], v[8:9]
	v_pk_add_f32 v[4:5], v[56:57], v[4:5]
	v_mul_f32_e32 v62, v63, v63
	v_mul_f32_e32 v6, v7, v7
	v_pk_add_f32 v[4:5], v[4:5], v[8:9]
	v_pk_add_f32 v[8:9], v[58:59], v[60:61]
	v_pk_add_f32 v[6:7], v[62:63], v[6:7]
	v_pk_add_f32 v[4:5], v[8:9], v[4:5]
	v_lshlrev_b32_e32 v33, 16, v1
	v_pk_add_f32 v[28:29], v[6:7], v[4:5]
	v_lshlrev_b32_e32 v5, 16, v0
	v_and_b32_e32 v7, 0xffff0000, v0
	v_mul_f32_e32 v4, v5, v5
	v_mul_f32_e32 v6, v7, v7
	v_pk_add_f32 v[46:47], v[4:5], v[6:7]
	v_and_b32_e32 v45, 0xffff0000, v1
	v_lshlrev_b32_e32 v27, 16, v2
	v_and_b32_e32 v31, 0xffff0000, v2
	v_lshlrev_b32_e32 v23, 16, v3
	v_and_b32_e32 v25, 0xffff0000, v3
	global_load_dwordx4 v[0:3], v[20:21], off offset:2288
	global_load_dwordx4 v[4:7], v[20:21], off offset:2272
	global_load_dwordx4 v[8:11], v[20:21], off offset:2256
	global_load_dwordx4 v[12:15], v[20:21], off offset:2240
	v_mul_f32_e32 v32, v33, v33
	v_mul_f32_e32 v44, v45, v45
	v_mul_f32_e32 v26, v27, v27
	v_mul_f32_e32 v30, v31, v31
	v_pk_add_f32 v[28:29], v[46:47], v[28:29]
	v_pk_add_f32 v[32:33], v[32:33], v[44:45]
	v_mul_f32_e32 v22, v23, v23
	v_mul_f32_e32 v24, v25, v25
	v_pk_add_f32 v[28:29], v[32:33], v[28:29]
	v_pk_add_f32 v[26:27], v[26:27], v[30:31]
	v_pk_add_f32 v[22:23], v[22:23], v[24:25]
	v_pk_add_f32 v[26:27], v[26:27], v[28:29]
	s_waitcnt vmcnt(3)
	v_lshlrev_b32_e32 v29, 16, v0
	v_pk_add_f32 v[22:23], v[22:23], v[26:27]
	s_waitcnt vmcnt(1)
	v_lshlrev_b32_e32 v59, 16, v8
	s_waitcnt vmcnt(0)
	v_lshlrev_b32_e32 v21, 16, v12
	v_and_b32_e32 v49, 0xffff0000, v12
	v_mul_f32_e32 v20, v21, v21
	v_mul_f32_e32 v48, v49, v49
	v_lshlrev_b32_e32 v51, 16, v13
	v_and_b32_e32 v13, 0xffff0000, v13
	v_mul_f32_e32 v50, v51, v51
	v_mul_f32_e32 v12, v13, v13
	v_lshlrev_b32_e32 v53, 16, v14
	v_and_b32_e32 v55, 0xffff0000, v14
	v_pk_add_f32 v[20:21], v[20:21], v[48:49]
	v_mul_f32_e32 v52, v53, v53
	v_mul_f32_e32 v54, v55, v55
	v_lshlrev_b32_e32 v57, 16, v15
	v_and_b32_e32 v15, 0xffff0000, v15
	v_pk_add_f32 v[20:21], v[20:21], v[22:23]
	v_pk_add_f32 v[12:13], v[50:51], v[12:13]
	v_mul_f32_e32 v56, v57, v57
	v_mul_f32_e32 v14, v15, v15
	v_and_b32_e32 v61, 0xffff0000, v8
	v_pk_add_f32 v[12:13], v[12:13], v[20:21]
	v_pk_add_f32 v[20:21], v[52:53], v[54:55]
	v_mul_f32_e32 v58, v59, v59
	v_mul_f32_e32 v60, v61, v61
	v_lshlrev_b32_e32 v63, 16, v9
	v_and_b32_e32 v9, 0xffff0000, v9
	v_pk_add_f32 v[12:13], v[20:21], v[12:13]
	v_pk_add_f32 v[14:15], v[56:57], v[14:15]
	v_mul_f32_e32 v62, v63, v63
	v_mul_f32_e32 v8, v9, v9
	v_lshlrev_b32_e32 v65, 16, v10
	v_and_b32_e32 v67, 0xffff0000, v10
	v_pk_add_f32 v[12:13], v[14:15], v[12:13]
	v_pk_add_f32 v[14:15], v[58:59], v[60:61]
	v_mul_f32_e32 v64, v65, v65
	v_mul_f32_e32 v66, v67, v67
	v_pk_add_f32 v[12:13], v[14:15], v[12:13]
	v_pk_add_f32 v[8:9], v[62:63], v[8:9]
	v_and_b32_e32 v15, 0xffff0000, v4
	v_pk_add_f32 v[8:9], v[8:9], v[12:13]
	v_pk_add_f32 v[12:13], v[64:65], v[66:67]
	v_mul_f32_e32 v14, v15, v15
	v_pk_add_f32 v[8:9], v[12:13], v[8:9]
	v_lshlrev_b32_e32 v13, 16, v11
	v_and_b32_e32 v11, 0xffff0000, v11
	v_mul_f32_e32 v12, v13, v13
	v_mul_f32_e32 v10, v11, v11
	v_pk_add_f32 v[10:11], v[12:13], v[10:11]
	v_lshlrev_b32_e32 v13, 16, v4
	v_mul_f32_e32 v12, v13, v13
	v_lshlrev_b32_e32 v21, 16, v5
	v_and_b32_e32 v5, 0xffff0000, v5
	v_mul_f32_e32 v20, v21, v21
	v_mul_f32_e32 v4, v5, v5
	v_lshlrev_b32_e32 v23, 16, v6
	v_and_b32_e32 v25, 0xffff0000, v6
	v_pk_add_f32 v[8:9], v[10:11], v[8:9]
	v_pk_add_f32 v[10:11], v[12:13], v[14:15]
	v_mul_f32_e32 v22, v23, v23
	v_mul_f32_e32 v24, v25, v25
	v_lshlrev_b32_e32 v27, 16, v7
	v_and_b32_e32 v7, 0xffff0000, v7
	v_pk_add_f32 v[8:9], v[10:11], v[8:9]
	v_pk_add_f32 v[4:5], v[20:21], v[4:5]
	v_mul_f32_e32 v26, v27, v27
	v_mul_f32_e32 v6, v7, v7
	v_and_b32_e32 v31, 0xffff0000, v0
	v_pk_add_f32 v[4:5], v[4:5], v[8:9]
	v_pk_add_f32 v[8:9], v[22:23], v[24:25]
	v_mul_f32_e32 v28, v29, v29
	v_mul_f32_e32 v30, v31, v31
	v_lshlrev_b32_e32 v33, 16, v1
	v_and_b32_e32 v1, 0xffff0000, v1
	v_pk_add_f32 v[4:5], v[8:9], v[4:5]
	v_pk_add_f32 v[6:7], v[26:27], v[6:7]
	v_mul_f32_e32 v32, v33, v33
	v_mul_f32_e32 v0, v1, v1
	v_lshlrev_b32_e32 v45, 16, v2
	v_and_b32_e32 v47, 0xffff0000, v2
	v_pk_add_f32 v[4:5], v[6:7], v[4:5]
	v_pk_add_f32 v[6:7], v[28:29], v[30:31]
	v_mul_f32_e32 v44, v45, v45
	v_mul_f32_e32 v46, v47, v47
	v_lshlrev_b32_e32 v49, 16, v3
	v_and_b32_e32 v3, 0xffff0000, v3
	v_pk_add_f32 v[4:5], v[6:7], v[4:5]
	v_pk_add_f32 v[0:1], v[32:33], v[0:1]
	v_mul_f32_e32 v48, v49, v49
	v_mul_f32_e32 v2, v3, v3
	v_pk_add_f32 v[0:1], v[0:1], v[4:5]
	v_pk_add_f32 v[4:5], v[44:45], v[46:47]
	v_pk_add_f32 v[2:3], v[48:49], v[2:3]
	v_pk_add_f32 v[0:1], v[4:5], v[0:1]
	s_nop 0
	v_pk_add_f32 v[0:1], v[2:3], v[0:1]
	ds_bpermute_b32 v3, v16, v1
	ds_bpermute_b32 v2, v16, v0
	v_or_b32_e32 v16, s27, v73
	v_lshlrev_b32_e32 v16, 1, v16
	s_waitcnt lgkmcnt(0)
	v_pk_add_f32 v[0:1], v[0:1], v[2:3]
	ds_bpermute_b32 v3, v41, v1
	ds_bpermute_b32 v2, v41, v0
	s_waitcnt lgkmcnt(0)
	v_pk_add_f32 v[0:1], v[0:1], v[2:3]
	s_nop 0
	v_pk_mul_f32 v[4:5], v[0:1], s[24:25] op_sel_hi:[1,0]
	s_lshl_b32 s24, s26, 8
	v_fma_f32 v0, -v5, v5, v4
	v_max_f32_e32 v0, 0, v0
	v_add_f32_e32 v0, 0x358637bd, v0
	v_cmp_gt_f32_e32 vcc, s55, v0
	v_mul_f32_e32 v1, 0x4b800000, v0
	s_nop 0
	v_cndmask_b32_e32 v0, v0, v1, vcc
	v_rsq_f32_e32 v0, v0
	s_nop 0
	v_mul_f32_e32 v1, 0x45800000, v0
	v_cndmask_b32_e32 v4, v0, v1, vcc
	v_lshl_add_u64 v[0:1], v[18:19], 0, s[24:25]
	v_lshl_add_u64 v[8:9], v[0:1], 0, v[42:43]
	s_lshl_b32 s24, s26, 9
	v_lshl_add_u64 v[6:7], v[38:39], 0, s[24:25]
	global_load_dwordx4 v[192:195], v[8:9], off offset:2048
	global_load_dwordx4 v[196:199], v[8:9], off offset:2064
	global_load_dwordx4 v[200:203], v[8:9], off offset:2080
	global_load_dwordx4 v[204:207], v[8:9], off offset:2096
	global_load_dwordx4 v[160:163], v[6:7], off
	global_load_dwordx4 v[164:167], v[6:7], off offset:16
	global_load_dwordx4 v[168:171], v[6:7], off offset:32
	global_load_dwordx4 v[172:175], v[6:7], off offset:48
	global_load_dwordx4 v[176:179], v[6:7], off offset:64
	global_load_dwordx4 v[180:183], v[6:7], off offset:80
	global_load_dwordx4 v[184:187], v[6:7], off offset:96
	global_load_dwordx4 v[188:191], v[6:7], off offset:112
	s_waitcnt vmcnt(0)
	s_ashr_i32 s24, s28, 31
	s_ashr_i32 s26, s29, 31
	s_add_u32 s28, s29, s28
	s_addc_u32 s29, s26, s24
	s_waitcnt vmcnt(1)
	v_lshlrev_b32_e32 v10, 16, v192
	v_sub_f32_e32 v10, v10, v5
	v_mul_f32_e32 v10, v10, v4
	s_waitcnt vmcnt(0)
	v_mul_f32_e32 v10, v160, v10
	v_cvt_pk_bf16_f32 v10, v10, v17
	ds_write_b16 v74, v10 offset:34816
	v_and_b32_e32 v0, 0xffff0000, v192
	v_sub_f32_e32 v0, v0, v5
	v_mul_f32_e32 v0, v0, v4
	s_waitcnt vmcnt(0)
	v_mul_f32_e32 v0, v161, v0
	v_cvt_pk_bf16_f32 v0, v0, v17
	ds_write_b16 v74, v0 offset:35088
	v_lshlrev_b32_e32 v0, 16, v193
	v_sub_f32_e32 v0, v0, v5
	v_mul_f32_e32 v0, v0, v4
	s_waitcnt vmcnt(0)
	v_mul_f32_e32 v0, v162, v0
	v_cvt_pk_bf16_f32 v0, v0, v17
	ds_write_b16 v74, v0 offset:35360
	v_and_b32_e32 v0, 0xffff0000, v193
	v_sub_f32_e32 v0, v0, v5
	v_mul_f32_e32 v0, v0, v4
	s_waitcnt vmcnt(0)
	v_mul_f32_e32 v0, v163, v0
	v_cvt_pk_bf16_f32 v0, v0, v17
	ds_write_b16 v74, v0 offset:35632
	v_lshlrev_b32_e32 v0, 16, v194
	v_sub_f32_e32 v0, v0, v5
	v_mul_f32_e32 v0, v0, v4
	s_waitcnt vmcnt(0)
	v_mul_f32_e32 v0, v164, v0
	v_cvt_pk_bf16_f32 v0, v0, v17
	ds_write_b16 v74, v0 offset:35904
	v_and_b32_e32 v0, 0xffff0000, v194
	v_sub_f32_e32 v0, v0, v5
	v_mul_f32_e32 v0, v0, v4
	s_waitcnt vmcnt(0)
	v_mul_f32_e32 v0, v165, v0
	v_cvt_pk_bf16_f32 v0, v0, v17
	ds_write_b16 v74, v0 offset:36176
	v_lshlrev_b32_e32 v0, 16, v195
	v_sub_f32_e32 v0, v0, v5
	v_mul_f32_e32 v0, v0, v4
	s_waitcnt vmcnt(0)
	v_mul_f32_e32 v0, v166, v0
	v_cvt_pk_bf16_f32 v0, v0, v17
	ds_write_b16 v74, v0 offset:36448
	v_and_b32_e32 v0, 0xffff0000, v195
	v_sub_f32_e32 v0, v0, v5
	v_mul_f32_e32 v0, v0, v4
	s_waitcnt vmcnt(0)
	v_mul_f32_e32 v0, v167, v0
	v_cvt_pk_bf16_f32 v0, v0, v17
	ds_write_b16 v74, v0 offset:36720
	s_waitcnt vmcnt(1)
	v_lshlrev_b32_e32 v10, 16, v196
	v_sub_f32_e32 v10, v10, v5
	v_mul_f32_e32 v10, v10, v4
	s_waitcnt vmcnt(0)
	v_mul_f32_e32 v10, v168, v10
	v_cvt_pk_bf16_f32 v10, v10, v17
	ds_write_b16 v75, v10 offset:34816
	v_and_b32_e32 v0, 0xffff0000, v196
	v_sub_f32_e32 v0, v0, v5
	v_mul_f32_e32 v0, v0, v4
	s_waitcnt vmcnt(0)
	v_mul_f32_e32 v0, v169, v0
	v_cvt_pk_bf16_f32 v0, v0, v17
	ds_write_b16 v75, v0 offset:35088
	v_lshlrev_b32_e32 v0, 16, v197
	v_sub_f32_e32 v0, v0, v5
	v_mul_f32_e32 v0, v0, v4
	s_waitcnt vmcnt(0)
	v_mul_f32_e32 v0, v170, v0
	v_cvt_pk_bf16_f32 v0, v0, v17
	ds_write_b16 v74, v0 offset:37536
	v_and_b32_e32 v0, 0xffff0000, v197
	v_sub_f32_e32 v0, v0, v5
	v_mul_f32_e32 v0, v0, v4
	s_waitcnt vmcnt(0)
	v_mul_f32_e32 v0, v171, v0
	v_cvt_pk_bf16_f32 v0, v0, v17
	ds_write_b16 v74, v0 offset:37808
	v_lshlrev_b32_e32 v0, 16, v198
	v_sub_f32_e32 v0, v0, v5
	v_mul_f32_e32 v0, v0, v4
	s_waitcnt vmcnt(0)
	v_mul_f32_e32 v0, v172, v0
	v_cvt_pk_bf16_f32 v0, v0, v17
	ds_write_b16 v74, v0 offset:38080
	v_and_b32_e32 v0, 0xffff0000, v198
	v_sub_f32_e32 v0, v0, v5
	v_mul_f32_e32 v0, v0, v4
	s_waitcnt vmcnt(0)
	v_mul_f32_e32 v0, v173, v0
	v_cvt_pk_bf16_f32 v0, v0, v17
	ds_write_b16 v74, v0 offset:38352
	v_lshlrev_b32_e32 v0, 16, v199
	v_sub_f32_e32 v0, v0, v5
	v_mul_f32_e32 v0, v0, v4
	s_waitcnt vmcnt(0)
	v_mul_f32_e32 v0, v174, v0
	v_cvt_pk_bf16_f32 v0, v0, v17
	ds_write_b16 v74, v0 offset:38624
	v_and_b32_e32 v0, 0xffff0000, v199
	v_sub_f32_e32 v0, v0, v5
	v_mul_f32_e32 v0, v0, v4
	s_waitcnt vmcnt(0)
	v_mul_f32_e32 v0, v175, v0
	v_cvt_pk_bf16_f32 v0, v0, v17
	ds_write_b16 v74, v0 offset:38896
	s_waitcnt vmcnt(1)
	v_lshlrev_b32_e32 v10, 16, v200
	v_sub_f32_e32 v10, v10, v5
	v_mul_f32_e32 v10, v10, v4
	s_waitcnt vmcnt(0)
	v_mul_f32_e32 v10, v176, v10
	v_cvt_pk_bf16_f32 v10, v10, v17
	ds_write_b16 v76, v10 offset:34816
	v_and_b32_e32 v0, 0xffff0000, v200
	v_sub_f32_e32 v0, v0, v5
	v_mul_f32_e32 v0, v0, v4
	s_waitcnt vmcnt(0)
	v_mul_f32_e32 v0, v177, v0
	v_cvt_pk_bf16_f32 v0, v0, v17
	ds_write_b16 v76, v0 offset:35088
	v_lshlrev_b32_e32 v0, 16, v201
	v_sub_f32_e32 v0, v0, v5
	v_mul_f32_e32 v0, v0, v4
	s_waitcnt vmcnt(0)
	v_mul_f32_e32 v0, v178, v0
	v_cvt_pk_bf16_f32 v0, v0, v17
	ds_write_b16 v74, v0 offset:39712
	v_and_b32_e32 v0, 0xffff0000, v201
	v_sub_f32_e32 v0, v0, v5
	v_mul_f32_e32 v0, v0, v4
	s_waitcnt vmcnt(0)
	v_mul_f32_e32 v0, v0, v179
	v_cvt_pk_bf16_f32 v0, v0, v17
	ds_write_b16 v74, v0 offset:39984
	v_lshlrev_b32_e32 v0, 16, v202
	v_sub_f32_e32 v0, v0, v5
	v_mul_f32_e32 v0, v0, v4
	s_waitcnt vmcnt(0)
	v_mul_f32_e32 v0, v0, v180
	v_cvt_pk_bf16_f32 v0, v0, v17
	ds_write_b16 v74, v0 offset:40256
	v_and_b32_e32 v0, 0xffff0000, v202
	v_sub_f32_e32 v0, v0, v5
	v_mul_f32_e32 v0, v0, v4
	s_waitcnt vmcnt(0)
	v_mul_f32_e32 v0, v0, v181
	v_cvt_pk_bf16_f32 v0, v0, v17
	ds_write_b16 v74, v0 offset:40528
	v_lshlrev_b32_e32 v0, 16, v203
	v_sub_f32_e32 v0, v0, v5
	v_mul_f32_e32 v0, v0, v4
	s_waitcnt vmcnt(0)
	v_mul_f32_e32 v0, v0, v182
	v_cvt_pk_bf16_f32 v0, v0, v17
	ds_write_b16 v74, v0 offset:40800
	v_and_b32_e32 v0, 0xffff0000, v203
	v_sub_f32_e32 v0, v0, v5
	v_mul_f32_e32 v0, v0, v4
	s_waitcnt vmcnt(0)
	v_mul_f32_e32 v0, v0, v183
	v_cvt_pk_bf16_f32 v0, v0, v17
	ds_write_b16 v74, v0 offset:41072
	s_waitcnt vmcnt(0)
	v_lshlrev_b32_e32 v8, 16, v204
	v_sub_f32_e32 v8, v8, v5
	v_mul_f32_e32 v8, v4, v8
	v_and_b32_e32 v0, 0xffff0000, v204
	v_sub_f32_e32 v0, v0, v5
	v_mul_f32_e32 v0, v4, v0
	s_waitcnt vmcnt(0)
	v_mul_f32_e32 v8, v184, v8
	v_cvt_pk_bf16_f32 v8, v8, v17
	ds_write_b16 v77, v8 offset:34816
	s_waitcnt vmcnt(0)
	v_mul_f32_e32 v0, v185, v0
	v_cvt_pk_bf16_f32 v0, v0, v17
	ds_write_b16 v77, v0 offset:35088
	v_lshlrev_b32_e32 v0, 16, v205
	v_sub_f32_e32 v0, v0, v5
	v_mul_f32_e32 v0, v4, v0
	s_waitcnt vmcnt(0)
	v_mul_f32_e32 v0, v0, v186
	v_cvt_pk_bf16_f32 v0, v0, v17
	ds_write_b16 v74, v0 offset:41888
	v_and_b32_e32 v0, 0xffff0000, v205
	v_sub_f32_e32 v0, v0, v5
	v_mul_f32_e32 v0, v4, v0
	s_waitcnt vmcnt(0)
	v_mul_f32_e32 v0, v0, v187
	v_cvt_pk_bf16_f32 v0, v0, v17
	ds_write_b16 v74, v0 offset:42160
	v_lshlrev_b32_e32 v0, 16, v206
	v_sub_f32_e32 v0, v0, v5
	v_mul_f32_e32 v0, v4, v0
	s_waitcnt vmcnt(0)
	v_mul_f32_e32 v0, v0, v188
	v_cvt_pk_bf16_f32 v0, v0, v17
	ds_write_b16 v74, v0 offset:42432
	v_and_b32_e32 v0, 0xffff0000, v206
	v_sub_f32_e32 v0, v0, v5
	v_mul_f32_e32 v0, v4, v0
	s_waitcnt vmcnt(0)
	v_mul_f32_e32 v0, v0, v189
	v_cvt_pk_bf16_f32 v0, v0, v17
	ds_write_b16 v74, v0 offset:42704
	v_lshlrev_b32_e32 v0, 16, v207
	v_sub_f32_e32 v0, v0, v5
	v_mul_f32_e32 v0, v4, v0
	s_waitcnt vmcnt(0)
	v_mul_f32_e32 v0, v0, v190
	v_cvt_pk_bf16_f32 v0, v0, v17
	ds_write_b16 v74, v0 offset:42976
	v_and_b32_e32 v0, 0xffff0000, v207
	v_sub_f32_e32 v0, v0, v5
	v_mul_f32_e32 v0, v4, v0
	s_waitcnt vmcnt(0)
	v_mul_f32_e32 v0, v0, v191
	v_cvt_pk_bf16_f32 v0, v0, v17
	ds_write_b16 v74, v0 offset:43248
	s_waitcnt lgkmcnt(0)
	s_barrier
	ds_read_b128 v[0:3], v36
	ds_read_b128 v[4:7], v78 offset:34816
	ds_read_b128 v[8:11], v78 offset:39168
	ds_read_b128 v[12:15], v78 offset:43520
	ds_read_b128 v[18:21], v78 offset:47872
	ds_read_b128 v[22:25], v78 offset:52224
	ds_read_b128 v[26:29], v78 offset:56576
	ds_read_b128 v[30:33], v78 offset:60928
	ds_read_b128 v[44:47], v78 offset:65280
	s_waitcnt lgkmcnt(7)
	v_mfma_f32_16x16x32_bf16 v[4:7], v[4:7], v[0:3], 0
	s_waitcnt lgkmcnt(6)
	v_mfma_f32_16x16x32_bf16 v[8:11], v[8:11], v[0:3], 0
	s_waitcnt lgkmcnt(5)
	v_mfma_f32_16x16x32_bf16 v[12:15], v[12:15], v[0:3], 0
	s_waitcnt lgkmcnt(4)
	v_mfma_f32_16x16x32_bf16 v[18:21], v[18:21], v[0:3], 0
	s_waitcnt lgkmcnt(3)
	v_mfma_f32_16x16x32_bf16 v[22:25], v[22:25], v[0:3], 0
	s_waitcnt lgkmcnt(2)
	v_mfma_f32_16x16x32_bf16 v[26:29], v[26:29], v[0:3], 0
	s_waitcnt lgkmcnt(1)
	v_mfma_f32_16x16x32_bf16 v[30:33], v[30:33], v[0:3], 0
	s_waitcnt lgkmcnt(0)
	v_mfma_f32_16x16x32_bf16 v[0:3], v[44:47], v[0:3], 0
	ds_read_b128 v[44:47], v36 offset:64
	ds_read_b128 v[48:51], v78 offset:34880
	s_waitcnt lgkmcnt(0)
	v_mfma_f32_16x16x32_bf16 v[4:7], v[48:51], v[44:47], v[4:7]
	ds_read_b128 v[48:51], v78 offset:39232
	s_waitcnt lgkmcnt(0)
	v_mfma_f32_16x16x32_bf16 v[8:11], v[48:51], v[44:47], v[8:11]
	ds_read_b128 v[48:51], v78 offset:43584
	s_waitcnt lgkmcnt(0)
	v_mfma_f32_16x16x32_bf16 v[12:15], v[48:51], v[44:47], v[12:15]
	ds_read_b128 v[48:51], v78 offset:47936
	s_waitcnt lgkmcnt(0)
	v_mfma_f32_16x16x32_bf16 v[18:21], v[48:51], v[44:47], v[18:21]
	ds_read_b128 v[48:51], v78 offset:52288
	s_waitcnt lgkmcnt(0)
	v_mfma_f32_16x16x32_bf16 v[22:25], v[48:51], v[44:47], v[22:25]
	ds_read_b128 v[48:51], v78 offset:56640
	s_waitcnt lgkmcnt(0)
	v_mfma_f32_16x16x32_bf16 v[26:29], v[48:51], v[44:47], v[26:29]
	ds_read_b128 v[48:51], v78 offset:60992
	s_waitcnt lgkmcnt(0)
	v_mfma_f32_16x16x32_bf16 v[30:33], v[48:51], v[44:47], v[30:33]
	ds_read_b128 v[48:51], v78 offset:65344
	s_waitcnt lgkmcnt(0)
	v_mfma_f32_16x16x32_bf16 v[0:3], v[48:51], v[44:47], v[0:3]
	ds_read_b128 v[44:47], v36 offset:128
	ds_read_b128 v[48:51], v78 offset:34944
	s_waitcnt lgkmcnt(0)
	v_mfma_f32_16x16x32_bf16 v[4:7], v[48:51], v[44:47], v[4:7]
	ds_read_b128 v[48:51], v78 offset:39296
	s_waitcnt lgkmcnt(0)
	v_mfma_f32_16x16x32_bf16 v[8:11], v[48:51], v[44:47], v[8:11]
	ds_read_b128 v[48:51], v78 offset:43648
	s_waitcnt lgkmcnt(0)
	v_mfma_f32_16x16x32_bf16 v[12:15], v[48:51], v[44:47], v[12:15]
	ds_read_b128 v[48:51], v78 offset:48000
	s_waitcnt lgkmcnt(0)
	v_mfma_f32_16x16x32_bf16 v[18:21], v[48:51], v[44:47], v[18:21]
	ds_read_b128 v[48:51], v78 offset:52352
	s_waitcnt lgkmcnt(0)
	v_mfma_f32_16x16x32_bf16 v[48:51], v[48:51], v[44:47], v[22:25]
	s_nop 2
	ds_read_b128 v[22:25], v78 offset:56704
	s_waitcnt lgkmcnt(0)
	v_mfma_f32_16x16x32_bf16 v[52:55], v[22:25], v[44:47], v[26:29]
	ds_read_b128 v[22:25], v78 offset:61056
	s_waitcnt lgkmcnt(0)
	v_mfma_f32_16x16x32_bf16 v[56:59], v[22:25], v[44:47], v[30:33]
	ds_read_b128 v[22:25], v78 offset:65408
	s_waitcnt lgkmcnt(0)
	v_mfma_f32_16x16x32_bf16 v[0:3], v[22:25], v[44:47], v[0:3]
	ds_read_b128 v[44:47], v36 offset:192
	ds_read_b128 v[22:25], v78 offset:35008
	s_waitcnt lgkmcnt(0)
	v_mfma_f32_16x16x32_bf16 v[30:33], v[22:25], v[44:47], v[4:7]
	s_nop 2
	ds_read_b128 v[4:7], v78 offset:39360
	s_waitcnt lgkmcnt(0)
	v_mfma_f32_16x16x32_bf16 v[26:29], v[4:7], v[44:47], v[8:11]
	ds_read_b128 v[4:7], v78 offset:43712
	s_waitcnt lgkmcnt(0)
	v_mfma_f32_16x16x32_bf16 v[22:25], v[4:7], v[44:47], v[12:15]
	ds_read_b128 v[4:7], v78 offset:48064
	s_waitcnt lgkmcnt(0)
	v_mfma_f32_16x16x32_bf16 v[18:21], v[4:7], v[44:47], v[18:21]
	ds_read_b128 v[4:7], v78 offset:52416
	s_waitcnt lgkmcnt(0)
	v_mfma_f32_16x16x32_bf16 v[12:15], v[4:7], v[44:47], v[48:51]
	ds_read_b128 v[4:7], v78 offset:56768
	s_nop 1
	ds_read_b128 v[48:51], v78 offset:65472
	s_waitcnt lgkmcnt(1)
	v_mfma_f32_16x16x32_bf16 v[8:11], v[4:7], v[44:47], v[52:55]
	ds_read_b128 v[4:7], v78 offset:61120
	s_waitcnt lgkmcnt(0)
	v_mfma_f32_16x16x32_bf16 v[4:7], v[4:7], v[44:47], v[56:59]
	v_mfma_f32_16x16x32_bf16 v[0:3], v[48:51], v[44:47], v[0:3]
	v_add_u32_e32 v44, s27, v37
	v_ashrrev_i32_e32 v45, 31, v44
	v_lshl_add_u64 v[44:45], v[44:45], 2, s[18:19]
	global_load_dword v41, v[44:45], off
	v_lshl_add_u64 v[44:45], s[28:29], 0, v[34:35]
	v_lshlrev_b64 v[46:47], 13, v[44:45]
	v_lshl_add_u64 v[46:47], s[22:23], 0, v[46:47]
	v_lshl_add_u64 v[46:47], v[46:47], 0, v[16:17]
	global_load_dwordx2 v[48:49], v[46:47], off offset:1024
	global_load_dwordx2 v[162:163], v[46:47], off offset:1056
	global_load_dwordx2 v[164:165], v[46:47], off offset:1088
	global_load_dwordx2 v[166:167], v[46:47], off offset:1120
	global_load_dwordx2 v[168:169], v[46:47], off offset:1152
	global_load_dwordx2 v[170:171], v[46:47], off offset:1184
	global_load_dwordx2 v[172:173], v[46:47], off offset:1216
	global_load_dwordx2 v[174:175], v[46:47], off offset:1248
	v_lshlrev_b64 v[44:45], 12, v[44:45]
	v_lshl_add_u64 v[44:45], s[0:1], 0, v[44:45]
	s_mov_b64 s[26:27], 0x23578400
	v_lshl_add_u64 v[44:45], v[44:45], 0, s[26:27]
	s_waitcnt vmcnt(1)
	v_add_f32_e32 v30, v30, v41
	v_add_f32_e32 v31, v31, v41
	v_add_f32_e32 v32, v32, v41
	v_add_f32_e32 v33, v33, v41
	v_add_f32_e32 v26, v26, v41
	s_waitcnt vmcnt(0)
	v_lshlrev_b32_e32 v43, 16, v48
	v_mul_f32_e32 v30, v30, v43
	v_and_b32_e32 v43, 0xffff0000, v48
	v_mul_f32_e32 v31, v31, v43
	v_cvt_pk_bf16_f32 v30, v30, v31
	v_lshlrev_b32_e32 v31, 16, v49
	v_mul_f32_e32 v31, v32, v31
	v_and_b32_e32 v32, 0xffff0000, v49
	v_mul_f32_e32 v32, v33, v32
	v_cvt_pk_bf16_f32 v31, v31, v32
	v_lshl_add_u64 v[32:33], v[44:45], 0, v[16:17]
	global_store_dwordx2 v[32:33], v[30:31], off
	v_add_f32_e32 v27, v27, v41
	v_add_f32_e32 v28, v28, v41
	v_add_f32_e32 v29, v29, v41
	v_add_f32_e32 v22, v22, v41
	v_add_f32_e32 v23, v23, v41
	v_add_f32_e32 v24, v24, v41
	v_add_f32_e32 v25, v25, v41
	v_add_f32_e32 v18, v18, v41
	v_add_f32_e32 v19, v19, v41
	v_add_f32_e32 v20, v20, v41
	v_add_f32_e32 v21, v21, v41
	v_add_f32_e32 v12, v12, v41
	v_add_f32_e32 v13, v13, v41
	v_add_f32_e32 v14, v14, v41
	v_add_f32_e32 v15, v15, v41
	v_add_f32_e32 v8, v8, v41
	v_add_f32_e32 v9, v9, v41
	v_add_f32_e32 v10, v10, v41
	v_add_f32_e32 v11, v11, v41
	v_add_f32_e32 v4, v4, v41
	v_add_f32_e32 v5, v5, v41
	v_add_f32_e32 v6, v6, v41
	v_add_f32_e32 v7, v7, v41
	v_add_f32_e32 v0, v41, v0
	v_add_f32_e32 v1, v41, v1
	v_add_f32_e32 v2, v41, v2
	v_add_f32_e32 v3, v41, v3
	v_lshlrev_b32_e32 v32, 16, v162
	v_and_b32_e32 v30, 0xffff0000, v162
	v_mul_f32_e32 v26, v26, v32
	v_mul_f32_e32 v27, v27, v30
	v_cvt_pk_bf16_f32 v26, v26, v27
	v_lshlrev_b32_e32 v27, 16, v163
	v_mul_f32_e32 v27, v28, v27
	v_and_b32_e32 v28, 0xffff0000, v163
	v_mul_f32_e32 v28, v29, v28
	v_cvt_pk_bf16_f32 v27, v27, v28
	v_or_b32_e32 v28, 32, v16
	v_mov_b32_e32 v29, v17
	v_lshl_add_u64 v[28:29], v[44:45], 0, v[28:29]
	global_store_dwordx2 v[28:29], v[26:27], off
	v_lshlrev_b32_e32 v28, 16, v164
	v_and_b32_e32 v26, 0xffff0000, v164
	v_mul_f32_e32 v22, v22, v28
	v_mul_f32_e32 v23, v23, v26
	v_cvt_pk_bf16_f32 v22, v22, v23
	v_lshlrev_b32_e32 v23, 16, v165
	v_mul_f32_e32 v23, v24, v23
	v_and_b32_e32 v24, 0xffff0000, v165
	v_mul_f32_e32 v24, v25, v24
	v_cvt_pk_bf16_f32 v23, v23, v24
	v_or_b32_e32 v24, 64, v16
	v_mov_b32_e32 v25, v17
	v_lshl_add_u64 v[24:25], v[44:45], 0, v[24:25]
	global_store_dwordx2 v[24:25], v[22:23], off
	v_lshlrev_b32_e32 v24, 16, v166
	v_and_b32_e32 v22, 0xffff0000, v166
	v_mul_f32_e32 v18, v18, v24
	v_mul_f32_e32 v19, v19, v22
	v_cvt_pk_bf16_f32 v18, v18, v19
	v_lshlrev_b32_e32 v19, 16, v167
	v_mul_f32_e32 v19, v20, v19
	v_and_b32_e32 v20, 0xffff0000, v167
	v_mul_f32_e32 v20, v21, v20
	v_cvt_pk_bf16_f32 v19, v19, v20
	v_or_b32_e32 v20, 0x60, v16
	v_mov_b32_e32 v21, v17
	v_lshl_add_u64 v[20:21], v[44:45], 0, v[20:21]
	global_store_dwordx2 v[20:21], v[18:19], off
	v_lshlrev_b32_e32 v20, 16, v168
	v_and_b32_e32 v18, 0xffff0000, v168
	v_mul_f32_e32 v12, v12, v20
	v_mul_f32_e32 v13, v13, v18
	v_cvt_pk_bf16_f32 v12, v12, v13
	v_lshlrev_b32_e32 v13, 16, v169
	v_mul_f32_e32 v13, v14, v13
	v_and_b32_e32 v14, 0xffff0000, v169
	v_mul_f32_e32 v14, v15, v14
	v_cvt_pk_bf16_f32 v13, v13, v14
	v_or_b32_e32 v14, 0x80, v16
	v_mov_b32_e32 v15, v17
	v_lshl_add_u64 v[14:15], v[44:45], 0, v[14:15]
	global_store_dwordx2 v[14:15], v[12:13], off
	v_lshlrev_b32_e32 v14, 16, v170
	v_and_b32_e32 v12, 0xffff0000, v170
	v_mul_f32_e32 v8, v8, v14
	v_mul_f32_e32 v9, v9, v12
	v_cvt_pk_bf16_f32 v8, v8, v9
	v_lshlrev_b32_e32 v9, 16, v171
	v_mul_f32_e32 v9, v10, v9
	v_and_b32_e32 v10, 0xffff0000, v171
	v_mul_f32_e32 v10, v11, v10
	v_cvt_pk_bf16_f32 v9, v9, v10
	v_or_b32_e32 v10, 0xa0, v16
	v_mov_b32_e32 v11, v17
	v_lshl_add_u64 v[10:11], v[44:45], 0, v[10:11]
	global_store_dwordx2 v[10:11], v[8:9], off
	v_lshlrev_b32_e32 v10, 16, v172
	v_and_b32_e32 v8, 0xffff0000, v172
	v_mul_f32_e32 v4, v4, v10
	v_mul_f32_e32 v5, v5, v8
	v_cvt_pk_bf16_f32 v4, v4, v5
	v_lshlrev_b32_e32 v5, 16, v173
	v_mul_f32_e32 v5, v6, v5
	v_and_b32_e32 v6, 0xffff0000, v173
	v_mul_f32_e32 v6, v7, v6
	v_cvt_pk_bf16_f32 v5, v5, v6
	v_or_b32_e32 v6, 0xc0, v16
	v_mov_b32_e32 v7, v17
	v_lshl_add_u64 v[6:7], v[44:45], 0, v[6:7]
	global_store_dwordx2 v[6:7], v[4:5], off
	v_or_b32_e32 v16, 0xe0, v16
	v_lshlrev_b32_e32 v6, 16, v174
	v_and_b32_e32 v4, 0xffff0000, v174
	v_mul_f32_e32 v0, v0, v6
	v_mul_f32_e32 v1, v1, v4
	v_cvt_pk_bf16_f32 v0, v0, v1
	v_lshlrev_b32_e32 v1, 16, v175
	v_mul_f32_e32 v1, v2, v1
	v_and_b32_e32 v2, 0xffff0000, v175
	v_mul_f32_e32 v2, v3, v2
	v_cvt_pk_bf16_f32 v1, v1, v2
	v_lshl_add_u64 v[2:3], v[44:45], 0, v[16:17]
	global_store_dwordx2 v[2:3], v[0:1], off
	s_barrier
